# v22: v19 + w_in GEMM epilogue runs staggered (no align barrier)
# baseline (speedup 1.0000x reference)
; #define PG8_BAR __builtin_amdgcn_s_barrier()
;     ...
;         if constexpr (ALIGN_EPI) { if (wr == 0) PG8_BAR; }
;         E(acc, cur, wr, wc, fr, fq);
;     __device__ __forceinline__ void operator()(const f32x4 (&acc)[2][2][4][2], const Unit& u, int wr, int wc, int fr, int fq) const {
;         const int row0 = u.pm * 256 + wr * 64 + fr;
;         if (u.pn < 26) {
;             const int col0 = u.pn * 256 + wc * 32 + 8 * fq;
.LBB0_521:
	s_nop 0
	v_lshl_add_u32 v142, s16, 8, v144
	s_cmp_gt_i32 s46, 25
	s_mov_b64 s[2:3], -1
	s_cbranch_scc0 .LBB0_519

; #define PG8_WAIT_V(n) asm volatile("s_waitcnt vmcnt(" #n ")" ::: "memory")
; #define PG8_BAR __builtin_amdgcn_s_barrier()
; __device__ __forceinline__ unsigned xb_add(unsigned* p, unsigned v) { return __hip_atomic_fetch_add(p, v, __ATOMIC_RELAXED, __HIP_MEMORY_SCOPE_AGENT); }
;     ...
;         if constexpr (ALIGN_EPI) { if (wr == 0) PG8_BAR; }
;         E(acc, cur, wr, wc, fr, fq);
;         if (ALIGN_EPI && arrive_word && ui + 1 == arrive_after) {
;             asm volatile("s_waitcnt vmcnt(0) lgkmcnt(0)" ::: "memory"); PG8_BAR;
;             if (tid == 0) { __builtin_amdgcn_fence(__ATOMIC_RELEASE, "agent"); asm volatile("s_waitcnt vmcnt(0)" ::: "memory");
;                 (void)__hip_atomic_fetch_add(arrive_word, 1u, __ATOMIC_RELAXED, __HIP_MEMORY_SCOPE_AGENT); } }
;         if (!has_next) break;
; #pragma unroll
;         for (int a = 0; a < 2; ++a)
; #pragma unroll
;             for (int b = 0; b < 2; ++b)
; #pragma unroll
;                 for (int m = 0; m < 4; ++m)
; #pragma unroll
;                     for (int n = 0; n < 2; ++n) acc[a][b][m][n] = (f32x4){0.f, 0.f, 0.f, 0.f};
;         cur = nxt; cA = nA; cB = nB; ++ui;
;         if constexpr (ALIGN_EPI) { if (wr == 1) PG8_BAR; }
;     }
;     PG8_WAIT_V(0);
;     if constexpr (!ALIGN_EPI) { if (wr == 0) PG8_BAR; }
;     PG8_BAR;
; __device__ __forceinline__ void xcd_barrier(const XcdBarrier& b) {
;     asm volatile("s_waitcnt vmcnt(0)" ::: "memory");
;     __syncthreads();
;     if (threadIdx.x == 0) {
;         unsigned* bar = b.bar;
;         __builtin_amdgcn_s_waitcnt(0);
;         unsigned nloc = b.st[0], nx = b.st[1];
;         if (nloc == 0u) { xcd_barrier_complete(bar, b.x, nloc, nx); b.st[0] = nloc; b.st[1] = nx; }
;         const unsigned old = xb_add(&bar[XB_XSUB(b.x)], 1u);
.LBB0_526:
	s_andn2_b64 vcc, exec, s[4:5]
	s_branch .LBB0_511
	s_barrier
	s_branch .LBB0_511
.LBB0_528:
	s_waitcnt vmcnt(0)
	s_movk_i32 s14, 0x3400
	s_movk_i32 s36, 0x1000
	s_mov_b64 s[28:29], 0x1c00
	s_and_b64 vcc, exec, s[8:9]
	s_cbranch_vccz .Lua_p5
	s_barrier
.Lua_p5:
	s_barrier
.LBB0_529:
	s_waitcnt vmcnt(0)
	s_waitcnt vmcnt(0)
	s_barrier
	s_mov_b64 s[4:5], exec
	v_readlane_b32 s0, v253, 4
	v_readlane_b32 s1, v253, 5
	s_and_b64 s[0:1], s[4:5], s[0:1]
	s_mov_b64 exec, s[0:1]
	s_cbranch_execz .LBB0_577
	v_readlane_b32 s0, v254, 12
	s_waitcnt vmcnt(0) expcnt(0) lgkmcnt(0)
	s_nop 0
	v_mov_b32_e32 v0, s0
	ds_read_b32 v3, v0
	v_readlane_b32 s0, v254, 13
	s_waitcnt lgkmcnt(0)
	v_cmp_ne_u32_e32 vcc, 0, v3
	v_mov_b32_e32 v0, s0
	ds_read_b32 v2, v0
	s_cbranch_vccnz .LBB0_545
	s_mov_b32 s0, 1
	s_branch .LBB0_533
